# phase-5 rmsnorm(x1): next item's row loads issued before the current item is reduced and stored
# baseline (speedup 1.0000x reference)
; DI unsigned pack2(float a, float b) { f32x2 v = {a, b}; bfx2 r = __builtin_convertvector(v, bfx2); return __builtin_bit_cast(unsigned, r); }
; #define FOR_BATCH(b) for (int b = X.pi; b < 8; b += X.npop)
; #define FOR_ITEMS(i, n) for (int i = X.rank; i < (n); i += X.cnt)
; DI void rmsnorm_rows(const float* __restrict__ src, const float* __restrict__ g, u16* __restrict__ dst, int item) {
;   const int lane = threadIdx.x & 63, w = threadIdx.x >> 6;
;   const size_t row = (size_t)item * 4 + w;
;   const float4* s4 = (const float4*)(src + row * 1024);
;   float4 v[4];
;   float ss = 0.f;
; #pragma unroll
;   for (int i = 0; i < 4; ++i) { v[i] = s4[lane + 64 * i]; ss += v[i].x * v[i].x + v[i].y * v[i].y + v[i].z * v[i].z + v[i].w * v[i].w; }
;   ss = wave_sum(ss);
;   const float sc = rsqrtf(ss * (1.f / 1024.f) + 1e-6f);
;   const float4* g4 = (const float4*)g;
; #pragma unroll
;   for (int i = 0; i < 4; ++i) {
;     float4 gg = g4[lane + 64 * i];
;     uint2 o = make_uint2(pack2(v[i].x * sc * gg.x, v[i].y * sc * gg.y), pack2(v[i].z * sc * gg.z, v[i].w * sc * gg.w));
;     *(uint2*)(dst + row * 1024 + (lane + 64 * i) * 4) = o;
;   }
; }
; __global__ void __launch_bounds__(256, 2) fwd_megakernel(Params p) {
;     ...
;   FOR_BATCH(b) FOR_ITEMS(i, 1024 * PM(128)) rmsnorm_rows(p.out, p.ln_ffn_g, (u16*)(p.ws + OFF_BUFA), b * 1024 + (i & 1023));
.LBB0_957:
	s_and_b64 vcc, exec, s[0:1]
	s_cbranch_vccnz .LBB0_956
	global_load_dwordx4 v[0:3], v[20:21], off
	global_load_dwordx4 v[4:7], v[20:21], off offset:1024
	global_load_dwordx4 v[8:11], v[20:21], off offset:2048
	global_load_dwordx4 v[12:15], v[20:21], off offset:3072
	v_cmp_lt_i32_e32 vcc, v31, v32
	s_lshl_b32 s4, s3, 10
	v_readlane_b32 s5, v253, 17
	v_cndmask_b32_e32 v25, v169, v31, vcc
	v_cmp_lt_i32_e32 vcc, v33, v32
	v_lshlrev_b32_e32 v38, 2, v25
	s_nop 0
	v_cndmask_b32_e32 v25, v169, v33, vcc
	v_cmp_lt_i32_e32 vcc, v34, v32
	v_lshlrev_b32_e32 v39, 2, v25
	s_nop 0
	v_cndmask_b32_e32 v25, v169, v34, vcc
	v_cmp_lt_i32_e32 vcc, v35, v32
	v_lshlrev_b32_e32 v40, 2, v25
	s_nop 0
	v_cndmask_b32_e32 v25, v169, v35, vcc
	v_cmp_lt_i32_e32 vcc, v36, v32
	v_lshlrev_b32_e32 v41, 2, v25
	s_nop 0
	v_cndmask_b32_e32 v25, v169, v36, vcc
	v_cmp_lt_i32_e32 vcc, v37, v32
	v_lshlrev_b32_e32 v42, 2, v25
	s_nop 0
	v_cndmask_b32_e32 v25, v169, v37, vcc
	v_lshlrev_b32_e32 v43, 2, v25
	s_and_b32 s6, s5, 0x3ff
	s_or_b32 s6, s6, s4
	s_ashr_i32 s7, s6, 31
	s_lshl_b64 s[6:7], s[6:7], 12
	v_lshl_add_u64 v[60:61], s[6:7], 0, v[16:17]
	v_lshl_add_u64 v[104:105], v[60:61], 2, v[22:23]
	global_load_dwordx4 v[86:89], v[104:105], off
	global_load_dwordx4 v[90:93], v[104:105], off offset:1024
	global_load_dwordx4 v[94:97], v[104:105], off offset:2048
	global_load_dwordx4 v[98:101], v[104:105], off offset:3072
	s_waitcnt vmcnt(0)
.LBB0_959:
	s_waitcnt vmcnt(4)
	v_mov_b32_e32 v44, v86
	v_mov_b32_e32 v45, v87
	v_mov_b32_e32 v46, v88
	v_mov_b32_e32 v47, v89
	v_mov_b32_e32 v48, v90
	v_mov_b32_e32 v49, v91
	v_mov_b32_e32 v50, v92
	v_mov_b32_e32 v51, v93
	v_mov_b32_e32 v52, v94
	v_mov_b32_e32 v53, v95
	v_mov_b32_e32 v54, v96
	v_mov_b32_e32 v55, v97
	v_mov_b32_e32 v56, v98
	v_mov_b32_e32 v57, v99
	v_mov_b32_e32 v58, v100
	v_mov_b32_e32 v59, v101
	v_mov_b32_e32 v25, v19
	v_lshl_add_u64 v[60:61], v[60:61], 1, s[22:23]
	v_lshl_add_u64 v[64:65], v[60:61], 0, v[24:25]
	v_mov_b32_e32 v27, v19
	v_lshl_add_u64 v[66:67], v[60:61], 0, v[26:27]
	v_mov_b32_e32 v29, v19
	v_lshl_add_u64 v[62:63], v[60:61], 0, v[18:19]
	v_lshl_add_u64 v[102:103], v[60:61], 0, v[28:29]
	s_add_i32 s5, s5, s21
	s_cmpk_gt_i32 s5, 0x3ff
	s_cbranch_scc1 .Lrms5_nopf
	s_and_b32 s6, s5, 0x3ff
	s_or_b32 s6, s6, s4
	s_ashr_i32 s7, s6, 31
	s_lshl_b64 s[6:7], s[6:7], 12
	v_lshl_add_u64 v[60:61], s[6:7], 0, v[16:17]
	v_lshl_add_u64 v[104:105], v[60:61], 2, v[22:23]
	global_load_dwordx4 v[86:89], v[104:105], off
	global_load_dwordx4 v[90:93], v[104:105], off offset:1024
	global_load_dwordx4 v[94:97], v[104:105], off offset:2048
	global_load_dwordx4 v[98:101], v[104:105], off offset:3072
.Lrms5_nopf:
	v_mov_b32_e32 v74, v45
	v_mov_b32_e32 v75, v49
	v_mov_b32_e32 v72, v44
	v_mov_b32_e32 v73, v48
	v_mov_b32_e32 v82, v53
	v_mov_b32_e32 v83, v57
	v_pk_mul_f32 v[74:75], v[74:75], v[74:75]
	v_mov_b32_e32 v68, v46
	v_mov_b32_e32 v69, v50
	v_mov_b32_e32 v80, v52
	v_mov_b32_e32 v81, v56
	v_pk_mul_f32 v[82:83], v[82:83], v[82:83]
	v_pk_fma_f32 v[72:73], v[72:73], v[72:73], v[74:75]
	v_mov_b32_e32 v70, v47
	v_mov_b32_e32 v71, v51
	v_mov_b32_e32 v76, v54
	v_mov_b32_e32 v77, v58
	v_pk_fma_f32 v[74:75], v[80:81], v[80:81], v[82:83]
	v_pk_fma_f32 v[68:69], v[68:69], v[68:69], v[72:73]
	v_mov_b32_e32 v78, v55
	v_mov_b32_e32 v79, v59
	v_pk_fma_f32 v[72:73], v[76:77], v[76:77], v[74:75]
	v_pk_fma_f32 v[68:69], v[70:71], v[70:71], v[68:69]
	v_pk_fma_f32 v[70:71], v[78:79], v[78:79], v[72:73]
	v_add_f32_e32 v25, v68, v69
	v_add_f32_e32 v25, v25, v70
	v_add_f32_e32 v25, v25, v71
	ds_bpermute_b32 v27, v38, v25
	s_waitcnt lgkmcnt(0)
	v_add_f32_e32 v25, v25, v27
	ds_bpermute_b32 v27, v39, v25
	s_waitcnt lgkmcnt(0)
	v_add_f32_e32 v25, v25, v27
	ds_bpermute_b32 v27, v40, v25
	s_waitcnt lgkmcnt(0)
	v_add_f32_e32 v25, v25, v27
	ds_bpermute_b32 v27, v41, v25
	s_waitcnt lgkmcnt(0)
	v_add_f32_e32 v25, v25, v27
	ds_bpermute_b32 v27, v42, v25
	s_waitcnt lgkmcnt(0)
	v_add_f32_e32 v25, v25, v27
	ds_bpermute_b32 v27, v43, v25
	s_waitcnt lgkmcnt(0)
	v_add_f32_e32 v25, v25, v27
	v_fmamk_f32 v25, v25, 0x3a800000, v30
	v_mul_f32_e32 v27, 0x4b800000, v25
	v_cmp_gt_f32_e32 vcc, s2, v25
	s_nop 1
	v_cndmask_b32_e32 v25, v25, v27, vcc
	v_rsq_f32_e32 v25, v25
	s_nop 0
	v_mul_f32_e32 v27, 0x45800000, v25
	v_cndmask_b32_e32 v68, v25, v27, vcc
	v_pk_mul_f32 v[44:45], v[44:45], v[68:69] op_sel_hi:[1,0]
	v_pk_mul_f32 v[46:47], v[46:47], v[68:69] op_sel_hi:[1,0]
	v_pk_mul_f32 v[48:49], v[48:49], v[68:69] op_sel_hi:[1,0]
	v_pk_mul_f32 v[50:51], v[50:51], v[68:69] op_sel_hi:[1,0]
	v_pk_mul_f32 v[52:53], v[52:53], v[68:69] op_sel_hi:[1,0]
	v_pk_mul_f32 v[54:55], v[54:55], v[68:69] op_sel_hi:[1,0]
	v_pk_mul_f32 v[56:57], v[56:57], v[68:69] op_sel_hi:[1,0]
	v_pk_mul_f32 v[58:59], v[58:59], v[68:69] op_sel_hi:[1,0]
	v_pk_mul_f32 v[44:45], v[0:1], v[44:45]
	v_pk_mul_f32 v[46:47], v[2:3], v[46:47]
	v_pk_mul_f32 v[48:49], v[4:5], v[48:49]
	v_pk_mul_f32 v[50:51], v[6:7], v[50:51]
	v_pk_mul_f32 v[52:53], v[52:53], v[8:9]
	v_pk_mul_f32 v[54:55], v[54:55], v[10:11]
	v_pk_mul_f32 v[56:57], v[56:57], v[12:13]
	v_pk_mul_f32 v[58:59], v[58:59], v[14:15]
	v_cvt_pk_f16_f32 v44, v44, v45
	v_cvt_pk_f16_f32 v45, v46, v47
	v_cvt_pk_f16_f32 v46, v48, v49
	v_cvt_pk_f16_f32 v47, v50, v51
	v_cvt_pk_f16_f32 v48, v52, v53
	v_cvt_pk_f16_f32 v49, v54, v55
	v_cvt_pk_f16_f32 v50, v56, v57
	v_cvt_pk_f16_f32 v51, v58, v59
	global_store_dwordx2 v[62:63], v[44:45], off
	global_store_dwordx2 v[64:65], v[46:47], off
	global_store_dwordx2 v[66:67], v[48:49], off
	global_store_dwordx2 v[102:103], v[50:51], off
	s_cmpk_gt_i32 s5, 0x3ff
	s_cbranch_scc0 .LBB0_959
	s_branch .LBB0_956
